# P3 gate epilogue loads hoisted + counted vmcnt; bias table loaded once per phase; attention epilogue tail loads hoisted
# speedup vs baseline: 1.0037x; 1.0037x over previous
.LBB0_299:
	s_andn2_b64 vcc, exec, s[0:1]
	s_waitcnt lgkmcnt(0)
	s_barrier
	s_cbranch_vccnz .LBB0_266
	ds_read2_b32 v[84:85], v82 offset1:32
	ds_read2_b32 v[86:87], v82 offset0:132 offset1:164
	v_add_u32_e32 v102, 0x1000, v82
	ds_read2_b32 v[90:91], v102 offset0:164 offset1:196
	v_add_u32_e32 v103, 0x1400, v82
	s_waitcnt lgkmcnt(2)
	v_fma_f32 v83, v50, v66, -v84
	s_waitcnt lgkmcnt(1)
	v_fma_f32 v84, v51, v70, -v86
	v_add_u32_e32 v86, 0x400, v82
	ds_read2_b32 v[50:51], v86 offset0:8 offset1:40
	ds_read2_b32 v[88:89], v86 offset0:140 offset1:172
	s_waitcnt lgkmcnt(2)
	v_fma_f32 v90, v55, v73, -v90
	ds_read2_b32 v[92:93], v103 offset0:172 offset1:204
	v_add_u32_e32 v104, 0x2000, v82
	s_waitcnt lgkmcnt(2)
	v_fma_f32 v50, v52, v69, -v50
	s_waitcnt lgkmcnt(1)
	v_fma_f32 v88, v53, v68, -v88
	ds_read2_b32 v[52:53], v102 offset0:32 offset1:64
	s_waitcnt lgkmcnt(1)
	v_fma_f32 v92, v57, v71, -v92
	ds_read2_b32 v[94:95], v104 offset0:196 offset1:228
	v_add_u32_e32 v105, 0x2400, v82
	ds_read2_b32 v[96:97], v105 offset0:204 offset1:236
	s_waitcnt lgkmcnt(2)
	v_fma_f32 v52, v54, v67, -v52
	ds_read2_b32 v[54:55], v103 offset0:40 offset1:72
	s_waitcnt lgkmcnt(2)
	v_fma_f32 v94, v59, v76, -v94
	v_add_u32_e32 v106, 0x3000, v82
	v_add_u32_e32 v107, 0x3200, v82
	s_waitcnt lgkmcnt(1)
	v_fma_f32 v96, v61, v74, -v96
	s_waitcnt lgkmcnt(0)
	v_fma_f32 v54, v56, v72, -v54
	ds_read2_b32 v[56:57], v104 offset0:64 offset1:96
	ds_read2_b32 v[98:99], v107 offset0:100 offset1:132
	v_fma_f32 v34, v34, v66, -v85
	ds_write2_b32 v82, v83, v34 offset1:32
	v_fma_f32 v34, v35, v70, -v87
	s_waitcnt lgkmcnt(2)
	v_fma_f32 v56, v58, v77, -v56
	ds_read2_b32 v[58:59], v105 offset0:72 offset1:104
	ds_write2_b32 v82, v84, v34 offset0:132 offset1:164
	v_fma_f32 v34, v36, v69, -v51
	v_add_u32_e32 v108, 0x3400, v82
	ds_write2_b32 v86, v50, v34 offset0:8 offset1:40
	s_waitcnt lgkmcnt(2)
	v_fma_f32 v58, v60, v75, -v58
	ds_read2_b32 v[60:61], v106 offset0:96 offset1:128
	v_fma_f32 v34, v37, v68, -v89
	v_fma_f32 v98, v63, v80, -v98
	ds_write2_b32 v86, v88, v34 offset0:140 offset1:172
	v_fma_f32 v34, v38, v67, -v53
	s_waitcnt lgkmcnt(1)
	v_fma_f32 v60, v62, v81, -v60
	ds_read2_b32 v[62:63], v108 offset0:104 offset1:136
	ds_write2_b32 v102, v52, v34 offset0:32 offset1:64
	v_fma_f32 v34, v39, v73, -v91
	ds_write2_b32 v102, v90, v34 offset0:164 offset1:196
	v_fma_f32 v34, v40, v72, -v55
	ds_write2_b32 v103, v54, v34 offset0:40 offset1:72
	v_fma_f32 v34, v41, v71, -v93
	ds_write2_b32 v103, v92, v34 offset0:172 offset1:204
	v_fma_f32 v34, v42, v77, -v57
	s_waitcnt lgkmcnt(4)
	v_fma_f32 v62, v64, v79, -v62
	v_add_u32_e32 v64, 0x3600, v82
	ds_write2_b32 v104, v56, v34 offset0:64 offset1:96
	v_fma_f32 v34, v43, v76, -v95
	ds_read2_b32 v[100:101], v64 offset0:108 offset1:140
	ds_write2_b32 v104, v94, v34 offset0:196 offset1:228
	v_fma_f32 v34, v44, v75, -v59
	ds_write2_b32 v105, v58, v34 offset0:72 offset1:104
	v_fma_f32 v34, v45, v74, -v97
	ds_write2_b32 v105, v96, v34 offset0:204 offset1:236
	v_fma_f32 v34, v46, v81, -v61
	ds_write2_b32 v106, v60, v34 offset0:96 offset1:128
	v_fma_f32 v34, v47, v80, -v99
	ds_write2_b32 v107, v98, v34 offset0:100 offset1:132
	v_fma_f32 v34, v48, v79, -v63
	s_waitcnt lgkmcnt(5)
	v_fma_f32 v65, v65, v78, -v100
	ds_write2_b32 v108, v62, v34 offset0:104 offset1:136
	v_fma_f32 v34, v49, v78, -v101
	ds_write2_b32 v64, v65, v34 offset0:108 offset1:140
	ds_read2_b32 v[34:35], v82 offset0:64 offset1:96
	ds_read2_b32 v[36:37], v82 offset0:196 offset1:228
	ds_read2_b32 v[38:39], v86 offset0:204 offset1:236
	v_add_u32_e32 v52, 0x1200, v82
	ds_read2_b32 v[40:41], v52 offset0:100 offset1:132
	s_waitcnt lgkmcnt(3)
	v_fma_f32 v34, v18, v66, -v34
	s_waitcnt lgkmcnt(2)
	v_fma_f32 v36, v19, v70, -v36
	ds_read2_b32 v[18:19], v86 offset0:72 offset1:104
	s_waitcnt lgkmcnt(2)
	v_fma_f32 v38, v21, v68, -v38
	v_add_u32_e32 v53, 0x1600, v82
	s_waitcnt lgkmcnt(1)
	v_fma_f32 v40, v23, v73, -v40
	ds_read2_b32 v[42:43], v53 offset0:108 offset1:140
	s_waitcnt lgkmcnt(1)
	v_fma_f32 v18, v20, v69, -v18
	ds_read2_b32 v[20:21], v102 offset0:96 offset1:128
	ds_read2_b32 v[44:45], v105 offset0:4 offset1:36
	v_add_u32_e32 v54, 0x2800, v82
	s_waitcnt lgkmcnt(2)
	v_fma_f32 v42, v25, v71, -v42
	ds_read2_b32 v[46:47], v54 offset0:12 offset1:44
	s_waitcnt lgkmcnt(2)
	v_fma_f32 v20, v22, v67, -v20
	ds_read2_b32 v[22:23], v103 offset0:104 offset1:136
	s_waitcnt lgkmcnt(2)
	v_fma_f32 v44, v27, v76, -v44
	ds_read2_b32 v[48:49], v108 offset0:36 offset1:68
	s_waitcnt lgkmcnt(2)
	v_fma_f32 v46, v29, v74, -v46
	v_fma_f32 v2, v2, v66, -v35
	s_waitcnt lgkmcnt(1)
	v_fma_f32 v22, v24, v72, -v22
	ds_read2_b32 v[24:25], v104 offset0:128 offset1:160
	ds_write2_b32 v82, v34, v2 offset0:64 offset1:96
	v_fma_f32 v2, v3, v70, -v37
	ds_write2_b32 v82, v36, v2 offset0:196 offset1:228
	v_fma_f32 v2, v4, v69, -v19
	s_waitcnt lgkmcnt(2)
	v_fma_f32 v24, v26, v77, -v24
	ds_read2_b32 v[26:27], v105 offset0:136 offset1:168
	ds_write2_b32 v86, v18, v2 offset0:72 offset1:104
	v_fma_f32 v2, v5, v68, -v39
	v_fma_f32 v48, v31, v80, -v48
	ds_write2_b32 v86, v38, v2 offset0:204 offset1:236
	s_waitcnt lgkmcnt(2)
	v_fma_f32 v26, v28, v75, -v26
	ds_read2_b32 v[28:29], v106 offset0:160 offset1:192
	v_fma_f32 v2, v6, v67, -v21
	ds_write2_b32 v102, v20, v2 offset0:96 offset1:128
	v_fma_f32 v2, v7, v73, -v41
	ds_write2_b32 v52, v40, v2 offset0:100 offset1:132
	s_waitcnt lgkmcnt(2)
	v_fma_f32 v28, v30, v81, -v28
	ds_read2_b32 v[30:31], v108 offset0:168 offset1:200
	v_fma_f32 v2, v8, v72, -v23
	ds_write2_b32 v103, v22, v2 offset0:104 offset1:136
	v_fma_f32 v2, v9, v71, -v43
	ds_write2_b32 v53, v42, v2 offset0:108 offset1:140
	v_fma_f32 v2, v10, v77, -v25
	s_waitcnt lgkmcnt(2)
	v_fma_f32 v30, v32, v79, -v30
	v_add_u32_e32 v32, 0x3800, v82
	ds_write2_b32 v104, v24, v2 offset0:128 offset1:160
	v_fma_f32 v2, v11, v76, -v45
	ds_read2_b32 v[50:51], v32 offset0:44 offset1:76
	ds_write2_b32 v105, v44, v2 offset0:4 offset1:36
	v_fma_f32 v2, v12, v75, -v27
	ds_write2_b32 v105, v26, v2 offset0:136 offset1:168
	v_fma_f32 v2, v13, v74, -v47
	ds_write2_b32 v54, v46, v2 offset0:12 offset1:44
	v_fma_f32 v2, v14, v81, -v29
	ds_write2_b32 v106, v28, v2 offset0:160 offset1:192
	v_fma_f32 v2, v15, v80, -v49
	ds_write2_b32 v108, v48, v2 offset0:36 offset1:68
	v_fma_f32 v2, v16, v79, -v31
	s_waitcnt lgkmcnt(5)
	v_fma_f32 v33, v33, v78, -v50
	ds_write2_b32 v108, v30, v2 offset0:168 offset1:200
	v_fma_f32 v2, v17, v78, -v51
	ds_write2_b32 v32, v33, v2 offset0:44 offset1:76
	v_mul_u32_u24_e32 v2, 0x210, v199
	v_lshlrev_b32_e32 v82, 8, v198
	s_waitcnt lgkmcnt(0)
	v_add3_u32 v71, s14, v2, v82
	ds_read_b128 v[50:53], v71
	ds_read_b128 v[46:49], v71 offset:16
	ds_read_b128 v[26:29], v71 offset:32
	ds_read_b128 v[18:21], v71 offset:48
	ds_read_b128 v[30:33], v71 offset:64
	s_waitcnt lgkmcnt(4)
	v_pk_mul_f32 v[2:3], v[52:53], v[52:53]
	v_pk_mul_f32 v[4:5], v[50:51], v[50:51]
	ds_read_b128 v[42:45], v71 offset:80
	v_pk_mov_b32 v[6:7], v[4:5], v[2:3] op_sel:[1,0]
	v_mov_b32_e32 v5, v3
	v_pk_add_f32 v[2:3], v[6:7], v[4:5]
	s_waitcnt lgkmcnt(4)
	v_pk_mul_f32 v[4:5], v[48:49], v[48:49]
	v_pk_mul_f32 v[6:7], v[46:47], v[46:47]
	v_pk_add_f32 v[2:3], v[2:3], v[2:3] op_sel:[0,1] op_sel_hi:[1,0]
	v_pk_mov_b32 v[8:9], v[6:7], v[4:5] op_sel:[1,0]
	v_mov_b32_e32 v7, v5
	v_pk_add_f32 v[4:5], v[8:9], v[6:7]
	s_waitcnt lgkmcnt(3)
	v_pk_mul_f32 v[6:7], v[28:29], v[28:29]
	v_pk_add_f32 v[4:5], v[4:5], v[4:5] op_sel:[0,1] op_sel_hi:[1,0]
	v_pk_mul_f32 v[8:9], v[26:27], v[26:27]
	s_waitcnt lgkmcnt(2)
	v_pk_mul_f32 v[10:11], v[20:21], v[20:21]
	v_pk_mul_f32 v[12:13], v[18:19], v[18:19]
	v_add_f32_e32 v8, v8, v9
	v_add_f32_e32 v6, v6, v7
	v_mov_b32_e32 v3, v12
	v_mov_b32_e32 v5, v13
	v_mov_b32_e32 v9, v10
	v_mov_b32_e32 v7, v11
	ds_read_b128 v[38:41], v71 offset:96
	v_pk_add_f32 v[2:3], v[2:3], v[4:5]
	v_pk_add_f32 v[4:5], v[8:9], v[6:7]
	s_waitcnt lgkmcnt(2)
	v_pk_mul_f32 v[6:7], v[30:31], v[30:31]
	v_pk_add_f32 v[2:3], v[2:3], v[4:5]
	v_pk_mul_f32 v[4:5], v[32:33], v[32:33]
	ds_read_b128 v[54:57], v71 offset:112
	v_pk_mov_b32 v[8:9], v[6:7], v[4:5] op_sel:[1,0]
	v_mov_b32_e32 v7, v5
	v_pk_add_f32 v[4:5], v[8:9], v[6:7]
	v_pk_add_f32 v[2:3], v[2:3], v[2:3] op_sel:[0,1] op_sel_hi:[1,0]
	v_pk_add_f32 v[4:5], v[4:5], v[4:5] op_sel:[0,1] op_sel_hi:[1,0]
	s_waitcnt lgkmcnt(2)
	v_pk_mul_f32 v[6:7], v[44:45], v[44:45]
	v_pk_mul_f32 v[8:9], v[42:43], v[42:43]
	s_waitcnt lgkmcnt(1)
	v_pk_mul_f32 v[10:11], v[40:41], v[40:41]
	v_pk_mul_f32 v[12:13], v[38:39], v[38:39]
	v_add_f32_e32 v8, v8, v9
	v_add_f32_e32 v6, v6, v7
	v_mov_b32_e32 v3, v12
	v_mov_b32_e32 v5, v13
	v_mov_b32_e32 v9, v10
	v_mov_b32_e32 v7, v11
	ds_read_b128 v[58:61], v71 offset:128
	ds_read_b128 v[62:65], v71 offset:144
	v_pk_add_f32 v[2:3], v[2:3], v[4:5]
	v_pk_add_f32 v[4:5], v[8:9], v[6:7]
	s_waitcnt lgkmcnt(2)
	v_pk_mul_f32 v[6:7], v[54:55], v[54:55]
	v_pk_add_f32 v[2:3], v[2:3], v[4:5]
	v_pk_mul_f32 v[4:5], v[56:57], v[56:57]
	ds_read_b128 v[34:37], v71 offset:160
	v_pk_mov_b32 v[8:9], v[6:7], v[4:5] op_sel:[1,0]
	v_mov_b32_e32 v7, v5
	v_pk_add_f32 v[4:5], v[8:9], v[6:7]
	v_pk_add_f32 v[2:3], v[2:3], v[2:3] op_sel:[0,1] op_sel_hi:[1,0]
	v_pk_add_f32 v[4:5], v[4:5], v[4:5] op_sel:[0,1] op_sel_hi:[1,0]
	s_waitcnt lgkmcnt(2)
	v_pk_mul_f32 v[6:7], v[60:61], v[60:61]
	v_pk_mul_f32 v[8:9], v[58:59], v[58:59]
	s_waitcnt lgkmcnt(1)
	v_pk_mul_f32 v[10:11], v[64:65], v[64:65]
	v_pk_mul_f32 v[12:13], v[62:63], v[62:63]
	v_add_f32_e32 v8, v8, v9
	v_add_f32_e32 v6, v6, v7
	v_mov_b32_e32 v3, v12
	v_mov_b32_e32 v5, v13
	v_mov_b32_e32 v9, v10
	v_mov_b32_e32 v7, v11
	ds_read_b128 v[22:25], v71 offset:176
	ds_read_b128 v[14:17], v71 offset:192
	v_pk_add_f32 v[2:3], v[2:3], v[4:5]
	v_pk_add_f32 v[4:5], v[8:9], v[6:7]
	s_waitcnt lgkmcnt(2)
	v_pk_mul_f32 v[6:7], v[34:35], v[34:35]
	v_pk_add_f32 v[2:3], v[2:3], v[4:5]
	v_pk_mul_f32 v[4:5], v[36:37], v[36:37]
	v_pk_add_f32 v[2:3], v[2:3], v[2:3] op_sel:[0,1] op_sel_hi:[1,0]
	v_pk_mov_b32 v[8:9], v[6:7], v[4:5] op_sel:[1,0]
	v_mov_b32_e32 v7, v5
	v_pk_add_f32 v[4:5], v[8:9], v[6:7]
	s_waitcnt lgkmcnt(1)
	v_pk_mul_f32 v[6:7], v[24:25], v[24:25]
	v_pk_add_f32 v[4:5], v[4:5], v[4:5] op_sel:[0,1] op_sel_hi:[1,0]
	v_pk_mul_f32 v[8:9], v[22:23], v[22:23]
	s_waitcnt lgkmcnt(0)
	v_pk_mul_f32 v[10:11], v[16:17], v[16:17]
	v_pk_mul_f32 v[12:13], v[14:15], v[14:15]
	v_add_f32_e32 v8, v8, v9
	v_add_f32_e32 v6, v6, v7
	v_mov_b32_e32 v3, v12
	v_mov_b32_e32 v5, v13
	v_mov_b32_e32 v9, v10
	v_mov_b32_e32 v7, v11
	ds_read_b128 v[10:13], v71 offset:208
	v_pk_add_f32 v[2:3], v[2:3], v[4:5]
	v_pk_add_f32 v[4:5], v[8:9], v[6:7]
	s_nop 0
	v_pk_add_f32 v[2:3], v[2:3], v[4:5]
	s_waitcnt lgkmcnt(0)
	v_pk_mul_f32 v[4:5], v[10:11], v[10:11]
	v_pk_add_f32 v[66:67], v[2:3], v[2:3] op_sel:[0,1] op_sel_hi:[1,0]
	v_pk_mul_f32 v[2:3], v[12:13], v[12:13]
	s_nop 0
	v_pk_mov_b32 v[6:7], v[4:5], v[2:3] op_sel:[1,0]
	v_mov_b32_e32 v5, v3
	v_pk_add_f32 v[2:3], v[6:7], v[4:5]
	ds_read_b128 v[6:9], v71 offset:224
	v_pk_add_f32 v[68:69], v[2:3], v[2:3] op_sel:[0,1] op_sel_hi:[1,0]
	s_waitcnt lgkmcnt(0)
	v_pk_mul_f32 v[2:3], v[8:9], v[8:9]
	v_pk_mul_f32 v[4:5], v[6:7], v[6:7]
	v_add_f32_e32 v72, v2, v3
	v_add_f32_e32 v70, v4, v5
	ds_read_b128 v[2:5], v71 offset:240
	s_waitcnt lgkmcnt(0)
	v_pk_mul_f32 v[74:75], v[4:5], v[4:5]
	v_pk_mul_f32 v[76:77], v[2:3], v[2:3]
	v_mov_b32_e32 v71, v74
	v_mov_b32_e32 v67, v76
	v_mov_b32_e32 v69, v77
	v_mov_b32_e32 v73, v75
	v_pk_add_f32 v[66:67], v[66:67], v[68:69]
	v_pk_add_f32 v[68:69], v[70:71], v[72:73]
	s_nop 0
	v_pk_add_f32 v[66:67], v[66:67], v[68:69]
	s_nop 0
	v_add_f32_e32 v66, v66, v67
	ds_bpermute_b32 v0, v0, v66
	s_waitcnt lgkmcnt(0)
	v_add_f32_e32 v0, v66, v0
	v_lshl_or_b32 v66, v198, 6, s67
	v_or_b32_e32 v186, v66, v186
	v_lshlrev_b64 v[66:67], 1, v[186:187]
	v_lshl_add_u64 v[80:81], s[18:19], 0, v[66:67]
	v_lshl_add_u64 v[78:79], s[16:17], 0, v[66:67]
	global_load_dwordx4 v[146:149], v[80:81], off
	global_load_dwordx4 v[150:153], v[80:81], off offset:16
	global_load_dwordx4 v[154:157], v[80:81], off offset:32
	global_load_dwordx4 v[158:161], v[80:81], off offset:48
	global_load_dwordx4 v[162:165], v[80:81], off offset:64
	global_load_dwordx4 v[166:169], v[80:81], off offset:80
	global_load_dwordx4 v[170:173], v[80:81], off offset:96
	global_load_dwordx4 v[174:177], v[80:81], off offset:112
	global_load_dwordx4 v[98:101], v82, s[42:43]
	global_load_dwordx4 v[102:105], v82, s[42:43] offset:16
	global_load_dwordx4 v[106:109], v82, s[42:43] offset:32
	global_load_dwordx4 v[110:113], v82, s[42:43] offset:48
	global_load_dwordx4 v[114:117], v82, s[42:43] offset:64
	global_load_dwordx4 v[118:121], v82, s[42:43] offset:80
	global_load_dwordx4 v[122:125], v82, s[42:43] offset:96
	global_load_dwordx4 v[126:129], v82, s[42:43] offset:112
	global_load_dwordx4 v[130:133], v82, s[42:43] offset:128
	global_load_dwordx4 v[134:137], v82, s[42:43] offset:144
	global_load_dwordx4 v[138:141], v82, s[42:43] offset:160
	global_load_dwordx4 v[142:145], v82, s[42:43] offset:176
	global_load_dwordx4 v[66:69], v82, s[42:43] offset:192
	global_load_dwordx4 v[70:73], v82, s[42:43] offset:208
	global_load_dwordx4 v[74:77], v82, s[42:43] offset:224
	global_load_dwordx4 v[84:87], v82, s[42:43] offset:240
	v_fmamk_f32 v0, v0, 0x3c000000, v211
	v_rsq_f32_e32 v0, v0
	s_nop 0
	v_mul_f32_e32 v0, v197, v0
	v_pk_mul_f32 v[50:51], v[50:51], v[0:1] op_sel_hi:[1,0]
	v_pk_mul_f32 v[46:47], v[46:47], v[0:1] op_sel_hi:[1,0]
	v_pk_mul_f32 v[48:49], v[48:49], v[0:1] op_sel_hi:[1,0]
	v_pk_mul_f32 v[52:53], v[52:53], v[0:1] op_sel_hi:[1,0]
	v_pk_mul_f32 v[26:27], v[26:27], v[0:1] op_sel_hi:[1,0]
	v_pk_mul_f32 v[18:19], v[18:19], v[0:1] op_sel_hi:[1,0]
	v_pk_mul_f32 v[20:21], v[20:21], v[0:1] op_sel_hi:[1,0]
	v_pk_mul_f32 v[28:29], v[28:29], v[0:1] op_sel_hi:[1,0]
	v_pk_mul_f32 v[30:31], v[30:31], v[0:1] op_sel_hi:[1,0]
	v_pk_mul_f32 v[42:43], v[42:43], v[0:1] op_sel_hi:[1,0]
	v_pk_mul_f32 v[32:33], v[32:33], v[0:1] op_sel_hi:[1,0]
	v_pk_mul_f32 v[44:45], v[44:45], v[0:1] op_sel_hi:[1,0]
	v_pk_mul_f32 v[38:39], v[38:39], v[0:1] op_sel_hi:[1,0]
	v_pk_mul_f32 v[40:41], v[40:41], v[0:1] op_sel_hi:[1,0]
	v_pk_mul_f32 v[34:35], v[34:35], v[0:1] op_sel_hi:[1,0]
	v_pk_mul_f32 v[22:23], v[22:23], v[0:1] op_sel_hi:[1,0]
	v_pk_mul_f32 v[36:37], v[36:37], v[0:1] op_sel_hi:[1,0]
	v_pk_mul_f32 v[24:25], v[24:25], v[0:1] op_sel_hi:[1,0]
	v_pk_mul_f32 v[14:15], v[14:15], v[0:1] op_sel_hi:[1,0]
	v_pk_mul_f32 v[10:11], v[10:11], v[0:1] op_sel_hi:[1,0]
	v_pk_mul_f32 v[12:13], v[12:13], v[0:1] op_sel_hi:[1,0]
	v_pk_mul_f32 v[16:17], v[16:17], v[0:1] op_sel_hi:[1,0]
	v_pk_mul_f32 v[6:7], v[6:7], v[0:1] op_sel_hi:[1,0]
	v_pk_mul_f32 v[2:3], v[2:3], v[0:1] op_sel_hi:[1,0]
	v_pk_mul_f32 v[4:5], v[4:5], v[0:1] op_sel_hi:[1,0]
	v_pk_mul_f32 v[8:9], v[8:9], v[0:1] op_sel_hi:[1,0]
	v_pk_mul_f32 v[54:55], v[54:55], v[0:1] op_sel_hi:[1,0]
	v_pk_mul_f32 v[56:57], v[56:57], v[0:1] op_sel_hi:[1,0]
	v_pk_mul_f32 v[58:59], v[58:59], v[0:1] op_sel_hi:[1,0]
	v_pk_mul_f32 v[60:61], v[60:61], v[0:1] op_sel_hi:[1,0]
	v_pk_mul_f32 v[62:63], v[62:63], v[0:1] op_sel_hi:[1,0]
	v_pk_mul_f32 v[64:65], v[64:65], v[0:1] op_sel_hi:[1,0]
	s_waitcnt vmcnt(14)
	v_pk_mul_f32 v[50:51], v[98:99], v[50:51]
	v_pk_mul_f32 v[52:53], v[100:101], v[52:53]
	v_pk_mul_f32 v[46:47], v[102:103], v[46:47]
	v_pk_mul_f32 v[48:49], v[104:105], v[48:49]
	v_lshlrev_b32_e32 v88, 16, v146
	v_and_b32_e32 v146, 0xffff0000, v146
	v_lshlrev_b32_e32 v89, 16, v147
	v_and_b32_e32 v147, 0xffff0000, v147
	v_lshlrev_b32_e32 v90, 16, v148
	v_and_b32_e32 v148, 0xffff0000, v148
	v_lshlrev_b32_e32 v91, 16, v149
	v_and_b32_e32 v149, 0xffff0000, v149
	v_mul_f32_e32 v88, v50, v88
	v_mul_f32_e32 v146, v51, v146
	v_mul_f32_e32 v89, v52, v89
	v_mul_f32_e32 v147, v53, v147
	v_mul_f32_e32 v90, v46, v90
	v_mul_f32_e32 v148, v47, v148
	v_mul_f32_e32 v91, v48, v91
	v_mul_f32_e32 v149, v49, v149
	v_cvt_pk_bf16_f32 v146, v88, v146
	v_cvt_pk_bf16_f32 v147, v89, v147
	v_cvt_pk_bf16_f32 v148, v90, v148
	v_cvt_pk_bf16_f32 v149, v91, v149
	global_store_dwordx4 v[78:79], v[146:149], off
	s_waitcnt vmcnt(13)
	v_pk_mul_f32 v[26:27], v[106:107], v[26:27]
	v_pk_mul_f32 v[28:29], v[108:109], v[28:29]
	v_pk_mul_f32 v[18:19], v[110:111], v[18:19]
	v_pk_mul_f32 v[20:21], v[112:113], v[20:21]
	v_lshlrev_b32_e32 v88, 16, v150
	v_and_b32_e32 v150, 0xffff0000, v150
	v_lshlrev_b32_e32 v89, 16, v151
	v_and_b32_e32 v151, 0xffff0000, v151
	v_lshlrev_b32_e32 v90, 16, v152
	v_and_b32_e32 v152, 0xffff0000, v152
	v_lshlrev_b32_e32 v91, 16, v153
	v_and_b32_e32 v153, 0xffff0000, v153
	v_mul_f32_e32 v88, v26, v88
	v_mul_f32_e32 v150, v27, v150
	v_mul_f32_e32 v89, v28, v89
	v_mul_f32_e32 v151, v29, v151
	v_mul_f32_e32 v90, v18, v90
	v_mul_f32_e32 v152, v19, v152
	v_mul_f32_e32 v91, v20, v91
	v_mul_f32_e32 v153, v21, v153
	v_cvt_pk_bf16_f32 v150, v88, v150
	v_cvt_pk_bf16_f32 v151, v89, v151
	v_cvt_pk_bf16_f32 v152, v90, v152
	v_cvt_pk_bf16_f32 v153, v91, v153
	global_store_dwordx4 v[78:79], v[150:153], off offset:16
	s_waitcnt vmcnt(12)
	v_pk_mul_f32 v[30:31], v[114:115], v[30:31]
	v_pk_mul_f32 v[32:33], v[116:117], v[32:33]
	v_pk_mul_f32 v[42:43], v[118:119], v[42:43]
	v_pk_mul_f32 v[44:45], v[120:121], v[44:45]
	v_lshlrev_b32_e32 v88, 16, v154
	v_and_b32_e32 v154, 0xffff0000, v154
	v_lshlrev_b32_e32 v89, 16, v155
	v_and_b32_e32 v155, 0xffff0000, v155
	v_lshlrev_b32_e32 v90, 16, v156
	v_and_b32_e32 v156, 0xffff0000, v156
	v_lshlrev_b32_e32 v91, 16, v157
	v_and_b32_e32 v157, 0xffff0000, v157
	v_mul_f32_e32 v88, v30, v88
	v_mul_f32_e32 v154, v31, v154
	v_mul_f32_e32 v89, v32, v89
	v_mul_f32_e32 v155, v33, v155
	v_mul_f32_e32 v90, v42, v90
	v_mul_f32_e32 v156, v43, v156
	v_mul_f32_e32 v91, v44, v91
	v_mul_f32_e32 v157, v45, v157
	v_cvt_pk_bf16_f32 v154, v88, v154
	v_cvt_pk_bf16_f32 v155, v89, v155
	v_cvt_pk_bf16_f32 v156, v90, v156
	v_cvt_pk_bf16_f32 v157, v91, v157
	global_store_dwordx4 v[78:79], v[154:157], off offset:32
	s_waitcnt vmcnt(11)
	v_pk_mul_f32 v[38:39], v[122:123], v[38:39]
	v_pk_mul_f32 v[40:41], v[124:125], v[40:41]
	v_pk_mul_f32 v[54:55], v[126:127], v[54:55]
	v_pk_mul_f32 v[56:57], v[128:129], v[56:57]
	v_lshlrev_b32_e32 v88, 16, v158
	v_and_b32_e32 v158, 0xffff0000, v158
	v_lshlrev_b32_e32 v89, 16, v159
	v_and_b32_e32 v159, 0xffff0000, v159
	v_lshlrev_b32_e32 v90, 16, v160
	v_and_b32_e32 v160, 0xffff0000, v160
	v_lshlrev_b32_e32 v91, 16, v161
	v_and_b32_e32 v161, 0xffff0000, v161
	v_mul_f32_e32 v88, v38, v88
	v_mul_f32_e32 v158, v39, v158
	v_mul_f32_e32 v89, v40, v89
	v_mul_f32_e32 v159, v41, v159
	v_mul_f32_e32 v90, v54, v90
	v_mul_f32_e32 v160, v55, v160
	v_mul_f32_e32 v91, v56, v91
	v_mul_f32_e32 v161, v57, v161
	v_cvt_pk_bf16_f32 v158, v88, v158
	v_cvt_pk_bf16_f32 v159, v89, v159
	v_cvt_pk_bf16_f32 v160, v90, v160
	v_cvt_pk_bf16_f32 v161, v91, v161
	global_store_dwordx4 v[78:79], v[158:161], off offset:48
	s_waitcnt vmcnt(10)
	v_pk_mul_f32 v[58:59], v[130:131], v[58:59]
	v_pk_mul_f32 v[60:61], v[132:133], v[60:61]
	v_pk_mul_f32 v[62:63], v[134:135], v[62:63]
	v_pk_mul_f32 v[64:65], v[136:137], v[64:65]
	v_lshlrev_b32_e32 v88, 16, v162
	v_and_b32_e32 v162, 0xffff0000, v162
	v_lshlrev_b32_e32 v89, 16, v163
	v_and_b32_e32 v163, 0xffff0000, v163
	v_lshlrev_b32_e32 v90, 16, v164
	v_and_b32_e32 v164, 0xffff0000, v164
	v_lshlrev_b32_e32 v91, 16, v165
	v_and_b32_e32 v165, 0xffff0000, v165
	v_mul_f32_e32 v88, v58, v88
	v_mul_f32_e32 v162, v59, v162
	v_mul_f32_e32 v89, v60, v89
	v_mul_f32_e32 v163, v61, v163
	v_mul_f32_e32 v90, v62, v90
	v_mul_f32_e32 v164, v63, v164
	v_mul_f32_e32 v91, v64, v91
	v_mul_f32_e32 v165, v65, v165
	v_cvt_pk_bf16_f32 v162, v88, v162
	v_cvt_pk_bf16_f32 v163, v89, v163
	v_cvt_pk_bf16_f32 v164, v90, v164
	v_cvt_pk_bf16_f32 v165, v91, v165
	global_store_dwordx4 v[78:79], v[162:165], off offset:64
	s_waitcnt vmcnt(9)
	v_pk_mul_f32 v[34:35], v[138:139], v[34:35]
	v_pk_mul_f32 v[36:37], v[140:141], v[36:37]
	v_pk_mul_f32 v[22:23], v[142:143], v[22:23]
	v_pk_mul_f32 v[24:25], v[144:145], v[24:25]
	v_lshlrev_b32_e32 v88, 16, v166
	v_and_b32_e32 v166, 0xffff0000, v166
	v_lshlrev_b32_e32 v89, 16, v167
	v_and_b32_e32 v167, 0xffff0000, v167
	v_lshlrev_b32_e32 v90, 16, v168
	v_and_b32_e32 v168, 0xffff0000, v168
	v_lshlrev_b32_e32 v91, 16, v169
	v_and_b32_e32 v169, 0xffff0000, v169
	v_mul_f32_e32 v88, v34, v88
	v_mul_f32_e32 v166, v35, v166
	v_mul_f32_e32 v89, v36, v89
	v_mul_f32_e32 v167, v37, v167
	v_mul_f32_e32 v90, v22, v90
	v_mul_f32_e32 v168, v23, v168
	v_mul_f32_e32 v91, v24, v91
	v_mul_f32_e32 v169, v25, v169
	v_cvt_pk_bf16_f32 v166, v88, v166
	v_cvt_pk_bf16_f32 v167, v89, v167
	v_cvt_pk_bf16_f32 v168, v90, v168
	v_cvt_pk_bf16_f32 v169, v91, v169
	global_store_dwordx4 v[78:79], v[166:169], off offset:80
	s_waitcnt vmcnt(8)
	v_pk_mul_f32 v[14:15], v[66:67], v[14:15]
	v_pk_mul_f32 v[16:17], v[68:69], v[16:17]
	v_pk_mul_f32 v[10:11], v[70:71], v[10:11]
	v_pk_mul_f32 v[12:13], v[72:73], v[12:13]
	v_lshlrev_b32_e32 v88, 16, v170
	v_and_b32_e32 v170, 0xffff0000, v170
	v_lshlrev_b32_e32 v89, 16, v171
	v_and_b32_e32 v171, 0xffff0000, v171
	v_lshlrev_b32_e32 v90, 16, v172
	v_and_b32_e32 v172, 0xffff0000, v172
	v_lshlrev_b32_e32 v91, 16, v173
	v_and_b32_e32 v173, 0xffff0000, v173
	v_mul_f32_e32 v88, v14, v88
	v_mul_f32_e32 v170, v15, v170
	v_mul_f32_e32 v89, v16, v89
	v_mul_f32_e32 v171, v17, v171
	v_mul_f32_e32 v90, v10, v90
	v_mul_f32_e32 v172, v11, v172
	v_mul_f32_e32 v91, v12, v91
	v_mul_f32_e32 v173, v13, v173
	v_cvt_pk_bf16_f32 v170, v88, v170
	v_cvt_pk_bf16_f32 v171, v89, v171
	v_cvt_pk_bf16_f32 v172, v90, v172
	v_cvt_pk_bf16_f32 v173, v91, v173
	global_store_dwordx4 v[78:79], v[170:173], off offset:96
	s_waitcnt vmcnt(7)
	v_pk_mul_f32 v[6:7], v[74:75], v[6:7]
	v_pk_mul_f32 v[8:9], v[76:77], v[8:9]
	v_pk_mul_f32 v[2:3], v[84:85], v[2:3]
	v_pk_mul_f32 v[4:5], v[86:87], v[4:5]
	v_lshlrev_b32_e32 v88, 16, v174
	v_and_b32_e32 v174, 0xffff0000, v174
	v_lshlrev_b32_e32 v89, 16, v175
	v_and_b32_e32 v175, 0xffff0000, v175
	v_lshlrev_b32_e32 v90, 16, v176
	v_and_b32_e32 v176, 0xffff0000, v176
	v_lshlrev_b32_e32 v91, 16, v177
	v_and_b32_e32 v177, 0xffff0000, v177
	v_mul_f32_e32 v88, v6, v88
	v_mul_f32_e32 v174, v7, v174
	v_mul_f32_e32 v89, v8, v89
	v_mul_f32_e32 v175, v9, v175
	v_mul_f32_e32 v90, v2, v90
	v_mul_f32_e32 v176, v3, v176
	v_mul_f32_e32 v91, v4, v91
	v_mul_f32_e32 v177, v5, v177
	v_cvt_pk_bf16_f32 v174, v88, v174
	v_cvt_pk_bf16_f32 v175, v89, v175
	v_cvt_pk_bf16_f32 v176, v90, v176
	v_cvt_pk_bf16_f32 v177, v91, v177
	global_store_dwordx4 v[78:79], v[174:177], off offset:112
	s_branch .LBB0_266
